# v11 plus counted wait in the P8 epilogue: rs and gate*rs computed while the conv-weight loads are in flight
# speedup vs baseline: 1.0048x; 1.0048x over previous
;     __device__ __forceinline__ void operator()(Acc& acc, const Unit& u, int wr, int wc, int fr, int fq) const {
;         const int row0 = u.pm * 256 + wr * 64 + fr, c0 = u.pn * 128 + wc * 32 + 8 * fq;
; #pragma unroll
;         for (int ai = 0; ai < 2; ++ai) {
;             float rs[4];
; #pragma unroll
;             for (int m = 0; m < 4; ++m) rs[m] = rsqrtf(rss[row0 + ai * 128 + m * 16] * (1.0f / D) + EPS);
;             const int blk = u.pm * 4 + ai * 2 + wr;
;             unsigned pk[4][4];
; #pragma unroll
;             for (int n = 0; n < 2; ++n) {
;                 const f32x4 w0 = *(const f32x4*)(cw + c0 + 4 * n), w1 = *(const f32x4*)(cw + FF + c0 + 4 * n), w2 = *(const f32x4*)(cw + 2 * FF + c0 + 4 * n), bb = *(const f32x4*)(cbias + c0 + 4 * n);
; #pragma unroll
;                 for (int jp = 0; jp < 2; ++jp) {
;                     const f32x2 w0p = {w0[2 * jp], w0[2 * jp + 1]}, w1p = {w1[2 * jp], w1[2 * jp + 1]}, w2p = {w2[2 * jp], w2[2 * jp + 1]}, bbp = {bb[2 * jp], bb[2 * jp + 1]};
;                     f32x2 gm[4], r1[4], r2[4];
; #pragma unroll
;                     for (int m = 0; m < 4; ++m) {
;                         gm[m] = (f32x2){acc[ai][0][m][n][2 * jp], acc[ai][0][m][n][2 * jp + 1]} * rs[m];
.LBB0_864:
	v_lshl_add_u32 v204, s58, 8, v153
	v_lshl_or_b32 v205, s59, 7, v187
	v_readlane_b32 s88, v250, 2
	v_readlane_b32 s89, v250, 3
	v_readlane_b32 s90, v250, 4
	v_readlane_b32 s91, v250, 5
	v_lshlrev_b32_e32 v207, 2, v204
	v_lshlrev_b32_e32 v216, 1, v205
	v_lshlrev_b32_e32 v205, 2, v205
	s_lshl_b32 s14, s58, 2
	s_add_i32 s14, s14, s33
	s_nop 0
	global_load_dword v172, v207, s[22:23]
	global_load_dword v173, v207, s[22:23] offset:64
	global_load_dword v174, v207, s[22:23] offset:128
	global_load_dword v175, v207, s[22:23] offset:192
	global_load_dword v178, v207, s[22:23] offset:512
	global_load_dword v179, v207, s[22:23] offset:576
	global_load_dword v180, v207, s[22:23] offset:640
	global_load_dword v181, v207, s[22:23] offset:704
	global_load_dwordx4 v[128:131], v205, s[88:89]
	global_load_dwordx4 v[132:135], v205, s[38:39]
	global_load_dwordx4 v[136:139], v205, s[40:41]
	global_load_dwordx4 v[140:143], v205, s[90:91]
	global_load_dwordx4 v[196:199], v205, s[88:89] offset:16
	global_load_dwordx4 v[200:203], v205, s[38:39] offset:16
	global_load_dwordx4 v[208:211], v205, s[40:41] offset:16
	global_load_dwordx4 v[212:215], v205, s[90:91] offset:16
	v_mad_u32_u24 v207, v204, s81, v216
	s_waitcnt vmcnt(8)
	v_fmamk_f32 v172, v172, 0x3a000000, v194
	v_fmamk_f32 v173, v173, 0x3a000000, v194
	v_fmamk_f32 v174, v174, 0x3a000000, v194
	v_fmamk_f32 v175, v175, 0x3a000000, v194
	v_fmamk_f32 v178, v178, 0x3a000000, v194
	v_fmamk_f32 v179, v179, 0x3a000000, v194
	v_fmamk_f32 v180, v180, 0x3a000000, v194
	v_fmamk_f32 v181, v181, 0x3a000000, v194
	v_rsq_f32_e32 v172, v172
	v_rsq_f32_e32 v173, v173
	v_rsq_f32_e32 v174, v174
	v_rsq_f32_e32 v175, v175
	v_rsq_f32_e32 v178, v178
	v_rsq_f32_e32 v179, v179
	v_rsq_f32_e32 v180, v180
	v_rsq_f32_e32 v181, v181
	v_mul_f32_e32 v182, 0xbf317218, v172
	v_mul_f32_e32 v183, 0xbf317218, v173
	v_mul_f32_e32 v184, 0xbf317218, v174
	v_mul_f32_e32 v185, 0xbf317218, v175
	v_mul_f32_e32 v186, 0xbf317218, v178
	v_mul_f32_e32 v188, 0xbf317218, v179
	v_mul_f32_e32 v190, 0xbf317218, v180
	v_mul_f32_e32 v192, 0xbf317218, v181
	v_mul_f32_e32 v84, v84, v172
	v_mul_f32_e32 v85, v85, v172
	v_mul_f32_e32 v86, v86, v172
	v_mul_f32_e32 v87, v87, v172
	v_mul_f32_e32 v124, v124, v173
	v_mul_f32_e32 v125, v125, v173
	v_mul_f32_e32 v126, v126, v173
	v_mul_f32_e32 v127, v127, v173
	v_mul_f32_e32 v120, v120, v174
	v_mul_f32_e32 v121, v121, v174
	v_mul_f32_e32 v122, v122, v174
	v_mul_f32_e32 v123, v123, v174
	v_mul_f32_e32 v68, v68, v175
	v_mul_f32_e32 v69, v69, v175
	v_mul_f32_e32 v70, v70, v175
	v_mul_f32_e32 v71, v71, v175
	v_mul_f32_e32 v24, v24, v178
	v_mul_f32_e32 v25, v25, v178
	v_mul_f32_e32 v26, v26, v178
	v_mul_f32_e32 v27, v27, v178
	v_mul_f32_e32 v60, v60, v179
	v_mul_f32_e32 v61, v61, v179
	v_mul_f32_e32 v62, v62, v179
	v_mul_f32_e32 v63, v63, v179
	v_mul_f32_e32 v56, v56, v180
	v_mul_f32_e32 v57, v57, v180
	v_mul_f32_e32 v58, v58, v180
	v_mul_f32_e32 v59, v59, v180
	v_mul_f32_e32 v4, v4, v181
	v_mul_f32_e32 v5, v5, v181
	v_mul_f32_e32 v6, v6, v181
	v_mul_f32_e32 v7, v7, v181
	v_mul_f32_e32 v80, v80, v172
	v_mul_f32_e32 v81, v81, v172
	v_mul_f32_e32 v82, v82, v172
	v_mul_f32_e32 v83, v83, v172
	v_mul_f32_e32 v104, v104, v173
	v_mul_f32_e32 v105, v105, v173
	v_mul_f32_e32 v106, v106, v173
	v_mul_f32_e32 v107, v107, v173
	v_mul_f32_e32 v100, v100, v174
	v_mul_f32_e32 v101, v101, v174
	v_mul_f32_e32 v102, v102, v174
	v_mul_f32_e32 v103, v103, v174
	v_mul_f32_e32 v64, v64, v175
	v_mul_f32_e32 v65, v65, v175
	v_mul_f32_e32 v66, v66, v175
	v_mul_f32_e32 v67, v67, v175
	v_mul_f32_e32 v16, v16, v178
	v_mul_f32_e32 v17, v17, v178
	v_mul_f32_e32 v18, v18, v178
	v_mul_f32_e32 v19, v19, v178
	v_mul_f32_e32 v40, v40, v179
	v_mul_f32_e32 v41, v41, v179
	v_mul_f32_e32 v42, v42, v179
	v_mul_f32_e32 v43, v43, v179
	v_mul_f32_e32 v36, v36, v180
	v_mul_f32_e32 v37, v37, v180
	v_mul_f32_e32 v38, v38, v180
	v_mul_f32_e32 v39, v39, v180
	v_mul_f32_e32 v0, v0, v181
	v_mul_f32_e32 v1, v1, v181
	v_mul_f32_e32 v2, v2, v181
	v_mul_f32_e32 v3, v3, v181
	s_waitcnt vmcnt(0)
	v_mul_f32_e32 v128, s42, v128
	v_mul_f32_e32 v129, s42, v129
	v_mul_f32_e32 v130, s42, v130
	v_mul_f32_e32 v131, s42, v131
	v_mul_f32_e32 v132, s42, v132
	v_mul_f32_e32 v133, s42, v133
	v_mul_f32_e32 v134, s42, v134
	v_mul_f32_e32 v135, s42, v135
	v_mul_f32_e32 v136, s42, v136
	v_mul_f32_e32 v137, s42, v137
	v_mul_f32_e32 v138, s42, v138
	v_mul_f32_e32 v139, s42, v139
	v_mul_f32_e32 v140, s42, v140
	v_mul_f32_e32 v141, s42, v141
	v_mul_f32_e32 v142, s42, v142
	v_mul_f32_e32 v143, s42, v143
	v_mul_f32_e32 v196, s42, v196
	v_mul_f32_e32 v197, s42, v197
	v_mul_f32_e32 v198, s42, v198
	v_mul_f32_e32 v199, s42, v199
	v_mul_f32_e32 v200, s42, v200
	v_mul_f32_e32 v201, s42, v201
	v_mul_f32_e32 v202, s42, v202
	v_mul_f32_e32 v203, s42, v203
	v_mul_f32_e32 v208, s42, v208
	v_mul_f32_e32 v209, s42, v209
	v_mul_f32_e32 v210, s42, v210
	v_mul_f32_e32 v211, s42, v211
	v_mul_f32_e32 v212, s42, v212
	v_mul_f32_e32 v213, s42, v213
	v_mul_f32_e32 v214, s42, v214
	v_mul_f32_e32 v215, s42, v215
	v_cndmask_b32_e64 v164, 0, v132, s[4:5]
	v_cndmask_b32_e64 v168, 0, v128, s[8:9]
	v_cndmask_b32_e64 v165, 0, v133, s[4:5]
	v_cndmask_b32_e64 v169, 0, v129, s[8:9]
	v_cndmask_b32_e64 v166, 0, v134, s[4:5]
	v_cndmask_b32_e64 v170, 0, v130, s[8:9]
	v_cndmask_b32_e64 v167, 0, v135, s[4:5]
	v_cndmask_b32_e64 v171, 0, v131, s[8:9]
	v_mul_f32_e32 v232, v76, v172
	v_mul_f32_e32 v233, v77, v172
	v_mul_f32_e32 v234, v78, v172
	v_mul_f32_e32 v235, v79, v172
	s_add_i32 s15, s14, 0
	v_lshl_add_u32 v228, s15, 1, v152
	v_lshl_add_u32 v229, s15, 1, v154
	v_mad_u32_u24 v230, v228, s83, v205
	v_mad_u32_u24 v231, v229, s83, v205
;     __device__ __forceinline__ void operator()(Acc& acc, const Unit& u, int wr, int wc, int fr, int fq) const {
;     ...
;                         const f32x2 q1 = m >= 1 ? r1[m >= 1 ? m - 1 : 0] : (f32x2){0.f, 0.f}, q2 = m >= 1 ? r2[m >= 1 ? m - 1 : 0] : (f32x2){0.f, 0.f};
;                         f32x2 p1, p2;
;                         p1.x = (fr >= 1) ? r1[m].x : q1.x; p1.y = (fr >= 1) ? r1[m].y : q1.y;
;                         p2.x = (fr >= 2) ? r2[m].x : q2.x; p2.y = (fr >= 2) ? r2[m].y : q2.y;
;                         const f32x2 a = w2p * gm[m] + (w1p * p1 + (w0p * p2 + bbp));
;                         const f32x2 na = a * (-1.4426950408889634f);
;                         f32x2 den; den.x = __builtin_amdgcn_exp2f(na.x); den.y = __builtin_amdgcn_exp2f(na.y);
;                         den = den + 1.0f;
;                         f32x2 rc; rc.x = __builtin_amdgcn_rcpf(den.x); rc.y = __builtin_amdgcn_rcpf(den.y);
;     ...
;             if (fr < 2) {
;                 const size_t o = ((size_t)blk * 2 + fr) * FF + c0;
;                 *(f32x4*)(gf + o) = acc[ai][0][0][0] * rs[0]; *(f32x4*)(gf + o + 4) = acc[ai][0][0][1] * rs[0];
;                 *(f32x4*)(uf + o) = acc[ai][1][0][0] * rs[0]; *(f32x4*)(uf + o + 4) = acc[ai][1][0][1] * rs[0];
;             }
;             if (fr >= 14) {
;                 const size_t o = ((size_t)blk * 2 + (fr - 14)) * FF + c0;
;                 *(f32x4*)(gl + o) = acc[ai][0][3][0] * rs[3]; *(f32x4*)(gl + o + 4) = acc[ai][0][3][1] * rs[3];
;             }
	s_mov_b64 exec, s[8:9]
	global_store_dwordx4 v230, v[84:87], s[86:87]
	global_store_dwordx4 v230, v[232:235], s[28:29]
	s_mov_b64 exec, s[10:11]
	global_store_dwordx4 v231, v[68:71], s[30:31]
	s_mov_b64 exec, -1
	v_fma_f32 v216, v136, v84, v140
	v_fma_f32 v217, v137, v85, v141
	v_fma_f32 v218, v138, v86, v142
	v_fma_f32 v219, v139, v87, v143
	v_fma_f32 v220, v136, v124, v140
	v_fma_f32 v221, v137, v125, v141
	v_fma_f32 v222, v138, v126, v142
	v_fma_f32 v223, v139, v127, v143
	v_fma_f32 v224, v136, v120, v140
	v_fma_f32 v225, v137, v121, v141
	v_fma_f32 v226, v138, v122, v142
	v_fma_f32 v227, v139, v123, v143
	v_fma_f32 v228, v136, v68, v140
	v_fma_f32 v229, v137, v69, v141
	v_fma_f32 v230, v138, v70, v142
	v_fma_f32 v231, v139, v71, v143
	v_fmac_f32_dpp v216, v84, v132 row_shr:1 row_mask:0xf bank_mask:0xf
	v_fmac_f32_dpp v217, v85, v133 row_shr:1 row_mask:0xf bank_mask:0xf
	v_fmac_f32_dpp v218, v86, v134 row_shr:1 row_mask:0xf bank_mask:0xf
	v_fmac_f32_dpp v219, v87, v135 row_shr:1 row_mask:0xf bank_mask:0xf
	v_fmac_f32_dpp v220, v124, v132 row_shr:1 row_mask:0xf bank_mask:0xf
	v_fmac_f32_dpp v221, v125, v133 row_shr:1 row_mask:0xf bank_mask:0xf
	v_fmac_f32_dpp v222, v126, v134 row_shr:1 row_mask:0xf bank_mask:0xf
	v_fmac_f32_dpp v223, v127, v135 row_shr:1 row_mask:0xf bank_mask:0xf
	v_fmac_f32_dpp v224, v120, v132 row_shr:1 row_mask:0xf bank_mask:0xf
	v_fmac_f32_dpp v225, v121, v133 row_shr:1 row_mask:0xf bank_mask:0xf
	v_fmac_f32_dpp v226, v122, v134 row_shr:1 row_mask:0xf bank_mask:0xf
	v_fmac_f32_dpp v227, v123, v135 row_shr:1 row_mask:0xf bank_mask:0xf
	v_fmac_f32_dpp v228, v68, v132 row_shr:1 row_mask:0xf bank_mask:0xf
	v_fmac_f32_dpp v229, v69, v133 row_shr:1 row_mask:0xf bank_mask:0xf
	v_fmac_f32_dpp v230, v70, v134 row_shr:1 row_mask:0xf bank_mask:0xf
	v_fmac_f32_dpp v231, v71, v135 row_shr:1 row_mask:0xf bank_mask:0xf
	v_fmac_f32_dpp v216, v84, v128 row_shr:2 row_mask:0xf bank_mask:0xf
	v_fmac_f32_dpp v217, v85, v129 row_shr:2 row_mask:0xf bank_mask:0xf
	v_fmac_f32_dpp v218, v86, v130 row_shr:2 row_mask:0xf bank_mask:0xf
	v_fmac_f32_dpp v219, v87, v131 row_shr:2 row_mask:0xf bank_mask:0xf
	v_fmac_f32_dpp v220, v124, v128 row_shr:2 row_mask:0xf bank_mask:0xf
	v_fmac_f32_dpp v221, v125, v129 row_shr:2 row_mask:0xf bank_mask:0xf
	v_fmac_f32_dpp v222, v126, v130 row_shr:2 row_mask:0xf bank_mask:0xf
	v_fmac_f32_dpp v223, v127, v131 row_shr:2 row_mask:0xf bank_mask:0xf
	v_fmac_f32_dpp v224, v120, v128 row_shr:2 row_mask:0xf bank_mask:0xf
	v_fmac_f32_dpp v225, v121, v129 row_shr:2 row_mask:0xf bank_mask:0xf
	v_fmac_f32_dpp v226, v122, v130 row_shr:2 row_mask:0xf bank_mask:0xf
	v_fmac_f32_dpp v227, v123, v131 row_shr:2 row_mask:0xf bank_mask:0xf
	v_fmac_f32_dpp v228, v68, v128 row_shr:2 row_mask:0xf bank_mask:0xf
	v_fmac_f32_dpp v229, v69, v129 row_shr:2 row_mask:0xf bank_mask:0xf
	v_fmac_f32_dpp v230, v70, v130 row_shr:2 row_mask:0xf bank_mask:0xf
	v_fmac_f32_dpp v231, v71, v131 row_shr:2 row_mask:0xf bank_mask:0xf
	v_fmac_f32_dpp v220, v84, v164 row_ror:1 row_mask:0xf bank_mask:0xf
	v_fmac_f32_dpp v221, v85, v165 row_ror:1 row_mask:0xf bank_mask:0xf
	v_fmac_f32_dpp v222, v86, v166 row_ror:1 row_mask:0xf bank_mask:0xf
	v_fmac_f32_dpp v223, v87, v167 row_ror:1 row_mask:0xf bank_mask:0xf
	v_fmac_f32_dpp v224, v124, v164 row_ror:1 row_mask:0xf bank_mask:0xf
	v_fmac_f32_dpp v225, v125, v165 row_ror:1 row_mask:0xf bank_mask:0xf
	v_fmac_f32_dpp v226, v126, v166 row_ror:1 row_mask:0xf bank_mask:0xf
	v_fmac_f32_dpp v227, v127, v167 row_ror:1 row_mask:0xf bank_mask:0xf
	v_fmac_f32_dpp v228, v120, v164 row_ror:1 row_mask:0xf bank_mask:0xf
	v_fmac_f32_dpp v229, v121, v165 row_ror:1 row_mask:0xf bank_mask:0xf
	v_fmac_f32_dpp v230, v122, v166 row_ror:1 row_mask:0xf bank_mask:0xf
	v_fmac_f32_dpp v231, v123, v167 row_ror:1 row_mask:0xf bank_mask:0xf
	v_fmac_f32_dpp v220, v84, v168 row_ror:2 row_mask:0xf bank_mask:0xf
	v_fmac_f32_dpp v221, v85, v169 row_ror:2 row_mask:0xf bank_mask:0xf
	v_fmac_f32_dpp v222, v86, v170 row_ror:2 row_mask:0xf bank_mask:0xf
	v_fmac_f32_dpp v223, v87, v171 row_ror:2 row_mask:0xf bank_mask:0xf
	v_fmac_f32_dpp v224, v124, v168 row_ror:2 row_mask:0xf bank_mask:0xf
	v_fmac_f32_dpp v225, v125, v169 row_ror:2 row_mask:0xf bank_mask:0xf
	v_fmac_f32_dpp v226, v126, v170 row_ror:2 row_mask:0xf bank_mask:0xf
	v_fmac_f32_dpp v227, v127, v171 row_ror:2 row_mask:0xf bank_mask:0xf
	v_fmac_f32_dpp v228, v120, v168 row_ror:2 row_mask:0xf bank_mask:0xf
	v_fmac_f32_dpp v229, v121, v169 row_ror:2 row_mask:0xf bank_mask:0xf
	v_fmac_f32_dpp v230, v122, v170 row_ror:2 row_mask:0xf bank_mask:0xf
	v_fmac_f32_dpp v231, v123, v171 row_ror:2 row_mask:0xf bank_mask:0xf
	v_exp_f32_e32 v84, v216
	v_exp_f32_e32 v85, v217
	v_exp_f32_e32 v86, v218
	v_exp_f32_e32 v87, v219
	v_exp_f32_e32 v124, v220
	v_exp_f32_e32 v125, v221
	v_exp_f32_e32 v126, v222
	v_exp_f32_e32 v127, v223
	v_exp_f32_e32 v120, v224
	v_exp_f32_e32 v121, v225
	v_exp_f32_e32 v122, v226
	v_exp_f32_e32 v123, v227
	v_exp_f32_e32 v68, v228
	v_exp_f32_e32 v69, v229
	v_exp_f32_e32 v70, v230
	v_exp_f32_e32 v71, v231
	v_add_f32_e32 v84, 1.0, v84
	v_add_f32_e32 v85, 1.0, v85
	v_add_f32_e32 v86, 1.0, v86
	v_add_f32_e32 v87, 1.0, v87
	v_add_f32_e32 v124, 1.0, v124
	v_add_f32_e32 v125, 1.0, v125
	v_add_f32_e32 v126, 1.0, v126
	v_add_f32_e32 v127, 1.0, v127
	v_add_f32_e32 v120, 1.0, v120
	v_add_f32_e32 v121, 1.0, v121
	v_add_f32_e32 v122, 1.0, v122
	v_add_f32_e32 v123, 1.0, v123
	v_add_f32_e32 v68, 1.0, v68
	v_add_f32_e32 v69, 1.0, v69
	v_add_f32_e32 v70, 1.0, v70
	v_add_f32_e32 v71, 1.0, v71
	v_rcp_f32_e32 v84, v84
	v_rcp_f32_e32 v85, v85
	v_rcp_f32_e32 v86, v86
	v_rcp_f32_e32 v87, v87
; __device__ __forceinline__ unsigned cvt_pk_bf16(float lo, float hi) { unsigned r; asm volatile("v_cvt_pk_bf16_f32 %0, %1, %2" : "=v"(r) : "v"(lo), "v"(hi)); return r; }
;     __device__ __forceinline__ void operator()(Acc& acc, const Unit& u, int wr, int wc, int fr, int fq) const {
;     ...
;                         const f32x2 a = w2p * gm[m] + (w1p * p1 + (w0p * p2 + bbp));
;                         const f32x2 na = a * (-1.4426950408889634f);
;                         f32x2 den; den.x = __builtin_amdgcn_exp2f(na.x); den.y = __builtin_amdgcn_exp2f(na.y);
;                         den = den + 1.0f;
;                         f32x2 rc; rc.x = __builtin_amdgcn_rcpf(den.x); rc.y = __builtin_amdgcn_rcpf(den.y);
;                         const f32x2 up = (f32x2){acc[ai][1][m][n][2 * jp], acc[ai][1][m][n][2 * jp + 1]} * rs[m];
;                         const f32x2 ov = (a * rc) * up;
;                         pk[m][2 * n + jp] = cvt_pk_bf16(ov.x, ov.y);
;                     }
;                 }
;             }
; #pragma unroll
;             for (int m = 0; m < 4; ++m) {
;                 const size_t row = (size_t)(row0 + ai * 128 + m * 16);
;                 if (!(m == 0 && fr < 2)) { u32x4 w; w.x = pk[m][0]; w.y = pk[m][1]; w.z = pk[m][2]; w.w = pk[m][3]; *(u32x4*)(act + row * FF + c0) = w; }
;             }
;             if (fr < 2) {
;                 const size_t o = ((size_t)blk * 2 + fr) * FF + c0;
;                 *(f32x4*)(gf + o) = acc[ai][0][0][0] * rs[0]; *(f32x4*)(gf + o + 4) = acc[ai][0][0][1] * rs[0];
;                 *(f32x4*)(uf + o) = acc[ai][1][0][0] * rs[0]; *(f32x4*)(uf + o + 4) = acc[ai][1][0][1] * rs[0];
;             }
;             if (fr >= 14) {
;                 const size_t o = ((size_t)blk * 2 + (fr - 14)) * FF + c0;
;                 *(f32x4*)(gl + o) = acc[ai][0][3][0] * rs[3]; *(f32x4*)(gl + o + 4) = acc[ai][0][3][1] * rs[3];
	v_rcp_f32_e32 v124, v124
	v_rcp_f32_e32 v125, v125
	v_rcp_f32_e32 v126, v126
	v_rcp_f32_e32 v127, v127
	v_rcp_f32_e32 v120, v120
	v_rcp_f32_e32 v121, v121
	v_rcp_f32_e32 v122, v122
	v_rcp_f32_e32 v123, v123
	v_rcp_f32_e32 v68, v68
	v_rcp_f32_e32 v69, v69
	v_rcp_f32_e32 v70, v70
	v_rcp_f32_e32 v71, v71
	v_mul_f32_e32 v76, v76, v182
	v_mul_f32_e32 v77, v77, v182
	v_mul_f32_e32 v78, v78, v182
	v_mul_f32_e32 v79, v79, v182
	v_mul_f32_e32 v116, v116, v183
	v_mul_f32_e32 v117, v117, v183
	v_mul_f32_e32 v118, v118, v183
	v_mul_f32_e32 v119, v119, v183
	v_mul_f32_e32 v112, v112, v184
	v_mul_f32_e32 v113, v113, v184
	v_mul_f32_e32 v114, v114, v184
	v_mul_f32_e32 v115, v115, v184
	v_mul_f32_e32 v108, v108, v185
	v_mul_f32_e32 v109, v109, v185
	v_mul_f32_e32 v110, v110, v185
	v_mul_f32_e32 v111, v111, v185
	v_mul_f32_e32 v216, v216, v84
	v_mul_f32_e32 v217, v217, v85
	v_mul_f32_e32 v218, v218, v86
	v_mul_f32_e32 v219, v219, v87
	v_mul_f32_e32 v220, v220, v124
	v_mul_f32_e32 v221, v221, v125
	v_mul_f32_e32 v222, v222, v126
	v_mul_f32_e32 v223, v223, v127
	v_mul_f32_e32 v224, v224, v120
	v_mul_f32_e32 v225, v225, v121
	v_mul_f32_e32 v226, v226, v122
	v_mul_f32_e32 v227, v227, v123
	v_mul_f32_e32 v228, v228, v68
	v_mul_f32_e32 v229, v229, v69
	v_mul_f32_e32 v230, v230, v70
	v_mul_f32_e32 v231, v231, v71
	v_mul_f32_e32 v216, v216, v76
	v_mul_f32_e32 v217, v217, v77
	v_mul_f32_e32 v218, v218, v78
	v_mul_f32_e32 v219, v219, v79
	v_mul_f32_e32 v220, v220, v116
	v_mul_f32_e32 v221, v221, v117
	v_mul_f32_e32 v222, v222, v118
	v_mul_f32_e32 v223, v223, v119
	v_mul_f32_e32 v224, v224, v112
	v_mul_f32_e32 v225, v225, v113
	v_mul_f32_e32 v226, v226, v114
	v_mul_f32_e32 v227, v227, v115
	v_mul_f32_e32 v228, v228, v108
	v_mul_f32_e32 v229, v229, v109
	v_mul_f32_e32 v230, v230, v110
	v_mul_f32_e32 v231, v231, v111
	v_cvt_pk_bf16_f32 v76, v216, v217
	v_cvt_pk_bf16_f32 v77, v218, v219
	v_cvt_pk_bf16_f32 v116, v220, v221
	v_cvt_pk_bf16_f32 v117, v222, v223
	v_cvt_pk_bf16_f32 v112, v224, v225
	v_cvt_pk_bf16_f32 v113, v226, v227
	v_cvt_pk_bf16_f32 v108, v228, v229
	v_cvt_pk_bf16_f32 v109, v230, v231
	v_mul_f32_e32 v232, v12, v178
	v_mul_f32_e32 v233, v13, v178
	v_mul_f32_e32 v234, v14, v178
	v_mul_f32_e32 v235, v15, v178
	s_add_i32 s15, s14, 2
	v_lshl_add_u32 v228, s15, 1, v152
	v_lshl_add_u32 v229, s15, 1, v154
	v_mad_u32_u24 v230, v228, s83, v205
	v_mad_u32_u24 v231, v229, s83, v205
	s_mov_b64 exec, s[8:9]
	global_store_dwordx4 v230, v[24:27], s[86:87]
	global_store_dwordx4 v230, v[232:235], s[28:29]
	s_mov_b64 exec, s[10:11]
	global_store_dwordx4 v231, v[4:7], s[30:31]
	s_mov_b64 exec, -1
	v_fma_f32 v216, v136, v24, v140
	v_fma_f32 v217, v137, v25, v141
	v_fma_f32 v218, v138, v26, v142
	v_fma_f32 v219, v139, v27, v143
	v_fma_f32 v220, v136, v60, v140
	v_fma_f32 v221, v137, v61, v141
	v_fma_f32 v222, v138, v62, v142
	v_fma_f32 v223, v139, v63, v143
	v_fma_f32 v224, v136, v56, v140
	v_fma_f32 v225, v137, v57, v141
	v_fma_f32 v226, v138, v58, v142
	v_fma_f32 v227, v139, v59, v143
	v_fma_f32 v228, v136, v4, v140
	v_fma_f32 v229, v137, v5, v141
	v_fma_f32 v230, v138, v6, v142
	v_fma_f32 v231, v139, v7, v143
	v_fmac_f32_dpp v216, v24, v132 row_shr:1 row_mask:0xf bank_mask:0xf
	v_fmac_f32_dpp v217, v25, v133 row_shr:1 row_mask:0xf bank_mask:0xf
	v_fmac_f32_dpp v218, v26, v134 row_shr:1 row_mask:0xf bank_mask:0xf
	v_fmac_f32_dpp v219, v27, v135 row_shr:1 row_mask:0xf bank_mask:0xf
	v_fmac_f32_dpp v220, v60, v132 row_shr:1 row_mask:0xf bank_mask:0xf
	v_fmac_f32_dpp v221, v61, v133 row_shr:1 row_mask:0xf bank_mask:0xf
	v_fmac_f32_dpp v222, v62, v134 row_shr:1 row_mask:0xf bank_mask:0xf
	v_fmac_f32_dpp v223, v63, v135 row_shr:1 row_mask:0xf bank_mask:0xf
	v_fmac_f32_dpp v224, v56, v132 row_shr:1 row_mask:0xf bank_mask:0xf
	v_fmac_f32_dpp v225, v57, v133 row_shr:1 row_mask:0xf bank_mask:0xf
	v_fmac_f32_dpp v226, v58, v134 row_shr:1 row_mask:0xf bank_mask:0xf
	v_fmac_f32_dpp v227, v59, v135 row_shr:1 row_mask:0xf bank_mask:0xf
	v_fmac_f32_dpp v228, v4, v132 row_shr:1 row_mask:0xf bank_mask:0xf
	v_fmac_f32_dpp v229, v5, v133 row_shr:1 row_mask:0xf bank_mask:0xf
	v_fmac_f32_dpp v230, v6, v134 row_shr:1 row_mask:0xf bank_mask:0xf
	v_fmac_f32_dpp v231, v7, v135 row_shr:1 row_mask:0xf bank_mask:0xf
	v_fmac_f32_dpp v216, v24, v128 row_shr:2 row_mask:0xf bank_mask:0xf
	v_fmac_f32_dpp v217, v25, v129 row_shr:2 row_mask:0xf bank_mask:0xf
	v_fmac_f32_dpp v218, v26, v130 row_shr:2 row_mask:0xf bank_mask:0xf
	v_fmac_f32_dpp v219, v27, v131 row_shr:2 row_mask:0xf bank_mask:0xf
	v_fmac_f32_dpp v220, v60, v128 row_shr:2 row_mask:0xf bank_mask:0xf
	v_fmac_f32_dpp v221, v61, v129 row_shr:2 row_mask:0xf bank_mask:0xf
	v_fmac_f32_dpp v222, v62, v130 row_shr:2 row_mask:0xf bank_mask:0xf
	v_fmac_f32_dpp v223, v63, v131 row_shr:2 row_mask:0xf bank_mask:0xf
	v_fmac_f32_dpp v224, v56, v128 row_shr:2 row_mask:0xf bank_mask:0xf
	v_fmac_f32_dpp v225, v57, v129 row_shr:2 row_mask:0xf bank_mask:0xf
	v_fmac_f32_dpp v226, v58, v130 row_shr:2 row_mask:0xf bank_mask:0xf
	v_fmac_f32_dpp v227, v59, v131 row_shr:2 row_mask:0xf bank_mask:0xf
	v_fmac_f32_dpp v228, v4, v128 row_shr:2 row_mask:0xf bank_mask:0xf
	v_fmac_f32_dpp v229, v5, v129 row_shr:2 row_mask:0xf bank_mask:0xf
	v_fmac_f32_dpp v230, v6, v130 row_shr:2 row_mask:0xf bank_mask:0xf
	v_fmac_f32_dpp v231, v7, v131 row_shr:2 row_mask:0xf bank_mask:0xf
	v_fmac_f32_dpp v220, v24, v164 row_ror:1 row_mask:0xf bank_mask:0xf
	v_fmac_f32_dpp v221, v25, v165 row_ror:1 row_mask:0xf bank_mask:0xf
	v_fmac_f32_dpp v222, v26, v166 row_ror:1 row_mask:0xf bank_mask:0xf
	v_fmac_f32_dpp v223, v27, v167 row_ror:1 row_mask:0xf bank_mask:0xf
; __device__ __forceinline__ unsigned cvt_pk_bf16(float lo, float hi) { unsigned r; asm volatile("v_cvt_pk_bf16_f32 %0, %1, %2" : "=v"(r) : "v"(lo), "v"(hi)); return r; }
;     __device__ __forceinline__ void operator()(Acc& acc, const Unit& u, int wr, int wc, int fr, int fq) const {
;     ...
;                     for (int m = 0; m < 4; ++m) {
;                         const f32x2 q1 = m >= 1 ? r1[m >= 1 ? m - 1 : 0] : (f32x2){0.f, 0.f}, q2 = m >= 1 ? r2[m >= 1 ? m - 1 : 0] : (f32x2){0.f, 0.f};
;                         f32x2 p1, p2;
;                         p1.x = (fr >= 1) ? r1[m].x : q1.x; p1.y = (fr >= 1) ? r1[m].y : q1.y;
;                         p2.x = (fr >= 2) ? r2[m].x : q2.x; p2.y = (fr >= 2) ? r2[m].y : q2.y;
;                         const f32x2 a = w2p * gm[m] + (w1p * p1 + (w0p * p2 + bbp));
;                         const f32x2 na = a * (-1.4426950408889634f);
;                         f32x2 den; den.x = __builtin_amdgcn_exp2f(na.x); den.y = __builtin_amdgcn_exp2f(na.y);
;                         den = den + 1.0f;
;                         f32x2 rc; rc.x = __builtin_amdgcn_rcpf(den.x); rc.y = __builtin_amdgcn_rcpf(den.y);
;                         const f32x2 up = (f32x2){acc[ai][1][m][n][2 * jp], acc[ai][1][m][n][2 * jp + 1]} * rs[m];
;                         const f32x2 ov = (a * rc) * up;
;                         pk[m][2 * n + jp] = cvt_pk_bf16(ov.x, ov.y);
;     ...
;             if (fr < 2) {
;                 const size_t o = ((size_t)blk * 2 + fr) * FF + c0;
;                 *(f32x4*)(gf + o) = acc[ai][0][0][0] * rs[0]; *(f32x4*)(gf + o + 4) = acc[ai][0][0][1] * rs[0];
;                 *(f32x4*)(uf + o) = acc[ai][1][0][0] * rs[0]; *(f32x4*)(uf + o + 4) = acc[ai][1][0][1] * rs[0];
;             }
;             if (fr >= 14) {
;                 const size_t o = ((size_t)blk * 2 + (fr - 14)) * FF + c0;
;                 *(f32x4*)(gl + o) = acc[ai][0][3][0] * rs[3]; *(f32x4*)(gl + o + 4) = acc[ai][0][3][1] * rs[3];
	v_fmac_f32_dpp v224, v60, v164 row_ror:1 row_mask:0xf bank_mask:0xf
	v_fmac_f32_dpp v225, v61, v165 row_ror:1 row_mask:0xf bank_mask:0xf
	v_fmac_f32_dpp v226, v62, v166 row_ror:1 row_mask:0xf bank_mask:0xf
	v_fmac_f32_dpp v227, v63, v167 row_ror:1 row_mask:0xf bank_mask:0xf
	v_fmac_f32_dpp v228, v56, v164 row_ror:1 row_mask:0xf bank_mask:0xf
	v_fmac_f32_dpp v229, v57, v165 row_ror:1 row_mask:0xf bank_mask:0xf
	v_fmac_f32_dpp v230, v58, v166 row_ror:1 row_mask:0xf bank_mask:0xf
	v_fmac_f32_dpp v231, v59, v167 row_ror:1 row_mask:0xf bank_mask:0xf
	v_fmac_f32_dpp v220, v24, v168 row_ror:2 row_mask:0xf bank_mask:0xf
	v_fmac_f32_dpp v221, v25, v169 row_ror:2 row_mask:0xf bank_mask:0xf
	v_fmac_f32_dpp v222, v26, v170 row_ror:2 row_mask:0xf bank_mask:0xf
	v_fmac_f32_dpp v223, v27, v171 row_ror:2 row_mask:0xf bank_mask:0xf
	v_fmac_f32_dpp v224, v60, v168 row_ror:2 row_mask:0xf bank_mask:0xf
	v_fmac_f32_dpp v225, v61, v169 row_ror:2 row_mask:0xf bank_mask:0xf
	v_fmac_f32_dpp v226, v62, v170 row_ror:2 row_mask:0xf bank_mask:0xf
	v_fmac_f32_dpp v227, v63, v171 row_ror:2 row_mask:0xf bank_mask:0xf
	v_fmac_f32_dpp v228, v56, v168 row_ror:2 row_mask:0xf bank_mask:0xf
	v_fmac_f32_dpp v229, v57, v169 row_ror:2 row_mask:0xf bank_mask:0xf
	v_fmac_f32_dpp v230, v58, v170 row_ror:2 row_mask:0xf bank_mask:0xf
	v_fmac_f32_dpp v231, v59, v171 row_ror:2 row_mask:0xf bank_mask:0xf
	v_exp_f32_e32 v24, v216
	v_exp_f32_e32 v25, v217
	v_exp_f32_e32 v26, v218
	v_exp_f32_e32 v27, v219
	v_exp_f32_e32 v60, v220
	v_exp_f32_e32 v61, v221
	v_exp_f32_e32 v62, v222
	v_exp_f32_e32 v63, v223
	v_exp_f32_e32 v56, v224
	v_exp_f32_e32 v57, v225
	v_exp_f32_e32 v58, v226
	v_exp_f32_e32 v59, v227
	v_exp_f32_e32 v4, v228
	v_exp_f32_e32 v5, v229
	v_exp_f32_e32 v6, v230
	v_exp_f32_e32 v7, v231
	v_add_f32_e32 v24, 1.0, v24
	v_add_f32_e32 v25, 1.0, v25
	v_add_f32_e32 v26, 1.0, v26
	v_add_f32_e32 v27, 1.0, v27
	v_add_f32_e32 v60, 1.0, v60
	v_add_f32_e32 v61, 1.0, v61
	v_add_f32_e32 v62, 1.0, v62
	v_add_f32_e32 v63, 1.0, v63
	v_add_f32_e32 v56, 1.0, v56
	v_add_f32_e32 v57, 1.0, v57
	v_add_f32_e32 v58, 1.0, v58
	v_add_f32_e32 v59, 1.0, v59
	v_add_f32_e32 v4, 1.0, v4
	v_add_f32_e32 v5, 1.0, v5
	v_add_f32_e32 v6, 1.0, v6
	v_add_f32_e32 v7, 1.0, v7
	v_rcp_f32_e32 v24, v24
	v_rcp_f32_e32 v25, v25
	v_rcp_f32_e32 v26, v26
	v_rcp_f32_e32 v27, v27
	v_rcp_f32_e32 v60, v60
	v_rcp_f32_e32 v61, v61
	v_rcp_f32_e32 v62, v62
	v_rcp_f32_e32 v63, v63
	v_rcp_f32_e32 v56, v56
	v_rcp_f32_e32 v57, v57
	v_rcp_f32_e32 v58, v58
	v_rcp_f32_e32 v59, v59
	v_rcp_f32_e32 v4, v4
	v_rcp_f32_e32 v5, v5
	v_rcp_f32_e32 v6, v6
	v_rcp_f32_e32 v7, v7
	v_mul_f32_e32 v12, v12, v186
	v_mul_f32_e32 v13, v13, v186
	v_mul_f32_e32 v14, v14, v186
	v_mul_f32_e32 v15, v15, v186
	v_mul_f32_e32 v52, v52, v188
	v_mul_f32_e32 v53, v53, v188
	v_mul_f32_e32 v54, v54, v188
	v_mul_f32_e32 v55, v55, v188
	v_mul_f32_e32 v48, v48, v190
	v_mul_f32_e32 v49, v49, v190
	v_mul_f32_e32 v50, v50, v190
	v_mul_f32_e32 v51, v51, v190
	v_mul_f32_e32 v44, v44, v192
	v_mul_f32_e32 v45, v45, v192
	v_mul_f32_e32 v46, v46, v192
	v_mul_f32_e32 v47, v47, v192
	v_mul_f32_e32 v216, v216, v24
	v_mul_f32_e32 v217, v217, v25
	v_mul_f32_e32 v218, v218, v26
	v_mul_f32_e32 v219, v219, v27
	v_mul_f32_e32 v220, v220, v60
	v_mul_f32_e32 v221, v221, v61
	v_mul_f32_e32 v222, v222, v62
	v_mul_f32_e32 v223, v223, v63
	v_mul_f32_e32 v224, v224, v56
	v_mul_f32_e32 v225, v225, v57
	v_mul_f32_e32 v226, v226, v58
	v_mul_f32_e32 v227, v227, v59
	v_mul_f32_e32 v228, v228, v4
	v_mul_f32_e32 v229, v229, v5
	v_mul_f32_e32 v230, v230, v6
	v_mul_f32_e32 v231, v231, v7
	v_mul_f32_e32 v216, v216, v12
	v_mul_f32_e32 v217, v217, v13
	v_mul_f32_e32 v218, v218, v14
	v_mul_f32_e32 v219, v219, v15
	v_mul_f32_e32 v220, v220, v52
	v_mul_f32_e32 v221, v221, v53
	v_mul_f32_e32 v222, v222, v54
	v_mul_f32_e32 v223, v223, v55
	v_mul_f32_e32 v224, v224, v48
	v_mul_f32_e32 v225, v225, v49
	v_mul_f32_e32 v226, v226, v50
	v_mul_f32_e32 v227, v227, v51
	v_mul_f32_e32 v228, v228, v44
	v_mul_f32_e32 v229, v229, v45
	v_mul_f32_e32 v230, v230, v46
	v_mul_f32_e32 v231, v231, v47
	v_cvt_pk_bf16_f32 v12, v216, v217
	v_cvt_pk_bf16_f32 v13, v218, v219
	v_cvt_pk_bf16_f32 v52, v220, v221
	v_cvt_pk_bf16_f32 v53, v222, v223
	v_cvt_pk_bf16_f32 v48, v224, v225
	v_cvt_pk_bf16_f32 v49, v226, v227
	v_cvt_pk_bf16_f32 v44, v228, v229
	v_cvt_pk_bf16_f32 v45, v230, v231
	v_cndmask_b32_e64 v164, 0, v200, s[4:5]
	v_cndmask_b32_e64 v168, 0, v196, s[8:9]
	v_cndmask_b32_e64 v165, 0, v201, s[4:5]
	v_cndmask_b32_e64 v169, 0, v197, s[8:9]
	v_cndmask_b32_e64 v166, 0, v202, s[4:5]
	v_cndmask_b32_e64 v170, 0, v198, s[8:9]
	v_cndmask_b32_e64 v167, 0, v203, s[4:5]
	v_cndmask_b32_e64 v171, 0, v199, s[8:9]
	v_mul_f32_e32 v232, v72, v172
	v_mul_f32_e32 v233, v73, v172
	v_mul_f32_e32 v234, v74, v172
	v_mul_f32_e32 v235, v75, v172
	s_add_i32 s15, s14, 0
	v_lshl_add_u32 v228, s15, 1, v152
	v_lshl_add_u32 v229, s15, 1, v154
	v_mad_u32_u24 v230, v228, s83, v205
	v_mad_u32_u24 v231, v229, s83, v205
	s_mov_b64 exec, s[8:9]
	global_store_dwordx4 v230, v[80:83], s[86:87] offset:16
	global_store_dwordx4 v230, v[232:235], s[28:29] offset:16
	s_mov_b64 exec, s[10:11]
	global_store_dwordx4 v231, v[64:67], s[30:31] offset:16
	s_mov_b64 exec, -1
	v_fma_f32 v216, v208, v80, v212
	v_fma_f32 v217, v209, v81, v213
	v_fma_f32 v218, v210, v82, v214
	v_fma_f32 v219, v211, v83, v215
	v_fma_f32 v220, v208, v104, v212
	v_fma_f32 v221, v209, v105, v213
	v_fma_f32 v222, v210, v106, v214
	v_fma_f32 v223, v211, v107, v215
	v_fma_f32 v224, v208, v100, v212
	v_fma_f32 v225, v209, v101, v213
	v_fma_f32 v226, v210, v102, v214
	v_fma_f32 v227, v211, v103, v215
	v_fma_f32 v228, v208, v64, v212
; __device__ __forceinline__ unsigned cvt_pk_bf16(float lo, float hi) { unsigned r; asm volatile("v_cvt_pk_bf16_f32 %0, %1, %2" : "=v"(r) : "v"(lo), "v"(hi)); return r; }
;     __device__ __forceinline__ void operator()(Acc& acc, const Unit& u, int wr, int wc, int fr, int fq) const {
;     ...
;                     for (int m = 0; m < 4; ++m) {
;                         const f32x2 q1 = m >= 1 ? r1[m >= 1 ? m - 1 : 0] : (f32x2){0.f, 0.f}, q2 = m >= 1 ? r2[m >= 1 ? m - 1 : 0] : (f32x2){0.f, 0.f};
;                         f32x2 p1, p2;
;                         p1.x = (fr >= 1) ? r1[m].x : q1.x; p1.y = (fr >= 1) ? r1[m].y : q1.y;
;                         p2.x = (fr >= 2) ? r2[m].x : q2.x; p2.y = (fr >= 2) ? r2[m].y : q2.y;
;                         const f32x2 a = w2p * gm[m] + (w1p * p1 + (w0p * p2 + bbp));
;                         const f32x2 na = a * (-1.4426950408889634f);
;                         f32x2 den; den.x = __builtin_amdgcn_exp2f(na.x); den.y = __builtin_amdgcn_exp2f(na.y);
;                         den = den + 1.0f;
;                         f32x2 rc; rc.x = __builtin_amdgcn_rcpf(den.x); rc.y = __builtin_amdgcn_rcpf(den.y);
;                         const f32x2 up = (f32x2){acc[ai][1][m][n][2 * jp], acc[ai][1][m][n][2 * jp + 1]} * rs[m];
;                         const f32x2 ov = (a * rc) * up;
;                         pk[m][2 * n + jp] = cvt_pk_bf16(ov.x, ov.y);
	v_fma_f32 v229, v209, v65, v213
	v_fma_f32 v230, v210, v66, v214
	v_fma_f32 v231, v211, v67, v215
	v_fmac_f32_dpp v216, v80, v200 row_shr:1 row_mask:0xf bank_mask:0xf
	v_fmac_f32_dpp v217, v81, v201 row_shr:1 row_mask:0xf bank_mask:0xf
	v_fmac_f32_dpp v218, v82, v202 row_shr:1 row_mask:0xf bank_mask:0xf
	v_fmac_f32_dpp v219, v83, v203 row_shr:1 row_mask:0xf bank_mask:0xf
	v_fmac_f32_dpp v220, v104, v200 row_shr:1 row_mask:0xf bank_mask:0xf
	v_fmac_f32_dpp v221, v105, v201 row_shr:1 row_mask:0xf bank_mask:0xf
	v_fmac_f32_dpp v222, v106, v202 row_shr:1 row_mask:0xf bank_mask:0xf
	v_fmac_f32_dpp v223, v107, v203 row_shr:1 row_mask:0xf bank_mask:0xf
	v_fmac_f32_dpp v224, v100, v200 row_shr:1 row_mask:0xf bank_mask:0xf
	v_fmac_f32_dpp v225, v101, v201 row_shr:1 row_mask:0xf bank_mask:0xf
	v_fmac_f32_dpp v226, v102, v202 row_shr:1 row_mask:0xf bank_mask:0xf
	v_fmac_f32_dpp v227, v103, v203 row_shr:1 row_mask:0xf bank_mask:0xf
	v_fmac_f32_dpp v228, v64, v200 row_shr:1 row_mask:0xf bank_mask:0xf
	v_fmac_f32_dpp v229, v65, v201 row_shr:1 row_mask:0xf bank_mask:0xf
	v_fmac_f32_dpp v230, v66, v202 row_shr:1 row_mask:0xf bank_mask:0xf
	v_fmac_f32_dpp v231, v67, v203 row_shr:1 row_mask:0xf bank_mask:0xf
	v_fmac_f32_dpp v216, v80, v196 row_shr:2 row_mask:0xf bank_mask:0xf
	v_fmac_f32_dpp v217, v81, v197 row_shr:2 row_mask:0xf bank_mask:0xf
	v_fmac_f32_dpp v218, v82, v198 row_shr:2 row_mask:0xf bank_mask:0xf
	v_fmac_f32_dpp v219, v83, v199 row_shr:2 row_mask:0xf bank_mask:0xf
	v_fmac_f32_dpp v220, v104, v196 row_shr:2 row_mask:0xf bank_mask:0xf
	v_fmac_f32_dpp v221, v105, v197 row_shr:2 row_mask:0xf bank_mask:0xf
	v_fmac_f32_dpp v222, v106, v198 row_shr:2 row_mask:0xf bank_mask:0xf
	v_fmac_f32_dpp v223, v107, v199 row_shr:2 row_mask:0xf bank_mask:0xf
	v_fmac_f32_dpp v224, v100, v196 row_shr:2 row_mask:0xf bank_mask:0xf
	v_fmac_f32_dpp v225, v101, v197 row_shr:2 row_mask:0xf bank_mask:0xf
	v_fmac_f32_dpp v226, v102, v198 row_shr:2 row_mask:0xf bank_mask:0xf
	v_fmac_f32_dpp v227, v103, v199 row_shr:2 row_mask:0xf bank_mask:0xf
	v_fmac_f32_dpp v228, v64, v196 row_shr:2 row_mask:0xf bank_mask:0xf
	v_fmac_f32_dpp v229, v65, v197 row_shr:2 row_mask:0xf bank_mask:0xf
	v_fmac_f32_dpp v230, v66, v198 row_shr:2 row_mask:0xf bank_mask:0xf
	v_fmac_f32_dpp v231, v67, v199 row_shr:2 row_mask:0xf bank_mask:0xf
	v_fmac_f32_dpp v220, v80, v164 row_ror:1 row_mask:0xf bank_mask:0xf
	v_fmac_f32_dpp v221, v81, v165 row_ror:1 row_mask:0xf bank_mask:0xf
	v_fmac_f32_dpp v222, v82, v166 row_ror:1 row_mask:0xf bank_mask:0xf
	v_fmac_f32_dpp v223, v83, v167 row_ror:1 row_mask:0xf bank_mask:0xf
	v_fmac_f32_dpp v224, v104, v164 row_ror:1 row_mask:0xf bank_mask:0xf
	v_fmac_f32_dpp v225, v105, v165 row_ror:1 row_mask:0xf bank_mask:0xf
	v_fmac_f32_dpp v226, v106, v166 row_ror:1 row_mask:0xf bank_mask:0xf
	v_fmac_f32_dpp v227, v107, v167 row_ror:1 row_mask:0xf bank_mask:0xf
	v_fmac_f32_dpp v228, v100, v164 row_ror:1 row_mask:0xf bank_mask:0xf
	v_fmac_f32_dpp v229, v101, v165 row_ror:1 row_mask:0xf bank_mask:0xf
	v_fmac_f32_dpp v230, v102, v166 row_ror:1 row_mask:0xf bank_mask:0xf
	v_fmac_f32_dpp v231, v103, v167 row_ror:1 row_mask:0xf bank_mask:0xf
	v_fmac_f32_dpp v220, v80, v168 row_ror:2 row_mask:0xf bank_mask:0xf
	v_fmac_f32_dpp v221, v81, v169 row_ror:2 row_mask:0xf bank_mask:0xf
	v_fmac_f32_dpp v222, v82, v170 row_ror:2 row_mask:0xf bank_mask:0xf
	v_fmac_f32_dpp v223, v83, v171 row_ror:2 row_mask:0xf bank_mask:0xf
	v_fmac_f32_dpp v224, v104, v168 row_ror:2 row_mask:0xf bank_mask:0xf
	v_fmac_f32_dpp v225, v105, v169 row_ror:2 row_mask:0xf bank_mask:0xf
	v_fmac_f32_dpp v226, v106, v170 row_ror:2 row_mask:0xf bank_mask:0xf
	v_fmac_f32_dpp v227, v107, v171 row_ror:2 row_mask:0xf bank_mask:0xf
	v_fmac_f32_dpp v228, v100, v168 row_ror:2 row_mask:0xf bank_mask:0xf
	v_fmac_f32_dpp v229, v101, v169 row_ror:2 row_mask:0xf bank_mask:0xf
	v_fmac_f32_dpp v230, v102, v170 row_ror:2 row_mask:0xf bank_mask:0xf
	v_fmac_f32_dpp v231, v103, v171 row_ror:2 row_mask:0xf bank_mask:0xf
	v_exp_f32_e32 v80, v216
	v_exp_f32_e32 v81, v217
	v_exp_f32_e32 v82, v218
	v_exp_f32_e32 v83, v219
	v_exp_f32_e32 v104, v220
	v_exp_f32_e32 v105, v221
	v_exp_f32_e32 v106, v222
	v_exp_f32_e32 v107, v223
	v_exp_f32_e32 v100, v224
	v_exp_f32_e32 v101, v225
	v_exp_f32_e32 v102, v226
	v_exp_f32_e32 v103, v227
	v_exp_f32_e32 v64, v228
	v_exp_f32_e32 v65, v229
	v_exp_f32_e32 v66, v230
	v_exp_f32_e32 v67, v231
	v_add_f32_e32 v80, 1.0, v80
	v_add_f32_e32 v81, 1.0, v81
	v_add_f32_e32 v82, 1.0, v82
	v_add_f32_e32 v83, 1.0, v83
	v_add_f32_e32 v104, 1.0, v104
	v_add_f32_e32 v105, 1.0, v105
	v_add_f32_e32 v106, 1.0, v106
	v_add_f32_e32 v107, 1.0, v107
	v_add_f32_e32 v100, 1.0, v100
	v_add_f32_e32 v101, 1.0, v101
	v_add_f32_e32 v102, 1.0, v102
	v_add_f32_e32 v103, 1.0, v103
	v_add_f32_e32 v64, 1.0, v64
	v_add_f32_e32 v65, 1.0, v65
	v_add_f32_e32 v66, 1.0, v66
	v_add_f32_e32 v67, 1.0, v67
	v_rcp_f32_e32 v80, v80
	v_rcp_f32_e32 v81, v81
	v_rcp_f32_e32 v82, v82
	v_rcp_f32_e32 v83, v83
	v_rcp_f32_e32 v104, v104
	v_rcp_f32_e32 v105, v105
	v_rcp_f32_e32 v106, v106
	v_rcp_f32_e32 v107, v107
	v_rcp_f32_e32 v100, v100
	v_rcp_f32_e32 v101, v101
	v_rcp_f32_e32 v102, v102
	v_rcp_f32_e32 v103, v103
	v_rcp_f32_e32 v64, v64
	v_rcp_f32_e32 v65, v65
	v_rcp_f32_e32 v66, v66
	v_rcp_f32_e32 v67, v67
	v_mul_f32_e32 v72, v72, v182
	v_mul_f32_e32 v73, v73, v182
	v_mul_f32_e32 v74, v74, v182
	v_mul_f32_e32 v75, v75, v182
	v_mul_f32_e32 v96, v96, v183
	v_mul_f32_e32 v97, v97, v183
	v_mul_f32_e32 v98, v98, v183
	v_mul_f32_e32 v99, v99, v183
	v_mul_f32_e32 v92, v92, v184
	v_mul_f32_e32 v93, v93, v184
	v_mul_f32_e32 v94, v94, v184
	v_mul_f32_e32 v95, v95, v184
; __device__ __forceinline__ unsigned cvt_pk_bf16(float lo, float hi) { unsigned r; asm volatile("v_cvt_pk_bf16_f32 %0, %1, %2" : "=v"(r) : "v"(lo), "v"(hi)); return r; }
;     __device__ __forceinline__ void operator()(Acc& acc, const Unit& u, int wr, int wc, int fr, int fq) const {
;     ...
;                         const f32x2 up = (f32x2){acc[ai][1][m][n][2 * jp], acc[ai][1][m][n][2 * jp + 1]} * rs[m];
;                         const f32x2 ov = (a * rc) * up;
;                         pk[m][2 * n + jp] = cvt_pk_bf16(ov.x, ov.y);
;                     }
;                 }
;             }
; #pragma unroll
;             for (int m = 0; m < 4; ++m) {
;                 const size_t row = (size_t)(row0 + ai * 128 + m * 16);
;                 if (!(m == 0 && fr < 2)) { u32x4 w; w.x = pk[m][0]; w.y = pk[m][1]; w.z = pk[m][2]; w.w = pk[m][3]; *(u32x4*)(act + row * FF + c0) = w; }
;             }
;             if (fr < 2) {
;                 const size_t o = ((size_t)blk * 2 + fr) * FF + c0;
;                 *(f32x4*)(gf + o) = acc[ai][0][0][0] * rs[0]; *(f32x4*)(gf + o + 4) = acc[ai][0][0][1] * rs[0];
;                 *(f32x4*)(uf + o) = acc[ai][1][0][0] * rs[0]; *(f32x4*)(uf + o + 4) = acc[ai][1][0][1] * rs[0];
;             }
;             if (fr >= 14) {
;                 const size_t o = ((size_t)blk * 2 + (fr - 14)) * FF + c0;
;                 *(f32x4*)(gl + o) = acc[ai][0][3][0] * rs[3]; *(f32x4*)(gl + o + 4) = acc[ai][0][3][1] * rs[3];
	v_mul_f32_e32 v88, v88, v185
	v_mul_f32_e32 v89, v89, v185
	v_mul_f32_e32 v90, v90, v185
	v_mul_f32_e32 v91, v91, v185
	v_mul_f32_e32 v216, v216, v80
	v_mul_f32_e32 v217, v217, v81
	v_mul_f32_e32 v218, v218, v82
	v_mul_f32_e32 v219, v219, v83
	v_mul_f32_e32 v220, v220, v104
	v_mul_f32_e32 v221, v221, v105
	v_mul_f32_e32 v222, v222, v106
	v_mul_f32_e32 v223, v223, v107
	v_mul_f32_e32 v224, v224, v100
	v_mul_f32_e32 v225, v225, v101
	v_mul_f32_e32 v226, v226, v102
	v_mul_f32_e32 v227, v227, v103
	v_mul_f32_e32 v228, v228, v64
	v_mul_f32_e32 v229, v229, v65
	v_mul_f32_e32 v230, v230, v66
	v_mul_f32_e32 v231, v231, v67
	v_mul_f32_e32 v216, v216, v72
	v_mul_f32_e32 v217, v217, v73
	v_mul_f32_e32 v218, v218, v74
	v_mul_f32_e32 v219, v219, v75
	v_mul_f32_e32 v220, v220, v96
	v_mul_f32_e32 v221, v221, v97
	v_mul_f32_e32 v222, v222, v98
	v_mul_f32_e32 v223, v223, v99
	v_mul_f32_e32 v224, v224, v92
	v_mul_f32_e32 v225, v225, v93
	v_mul_f32_e32 v226, v226, v94
	v_mul_f32_e32 v227, v227, v95
	v_mul_f32_e32 v228, v228, v88
	v_mul_f32_e32 v229, v229, v89
	v_mul_f32_e32 v230, v230, v90
	v_mul_f32_e32 v231, v231, v91
	v_cvt_pk_bf16_f32 v78, v216, v217
	v_cvt_pk_bf16_f32 v79, v218, v219
	v_cvt_pk_bf16_f32 v118, v220, v221
	v_cvt_pk_bf16_f32 v119, v222, v223
	v_cvt_pk_bf16_f32 v114, v224, v225
	v_cvt_pk_bf16_f32 v115, v226, v227
	v_cvt_pk_bf16_f32 v110, v228, v229
	v_cvt_pk_bf16_f32 v111, v230, v231
	s_mov_b32 s16, s26
	s_mov_b32 s17, s27
	s_mov_b64 exec, s[6:7]
	global_store_dwordx4 v207, v[76:79], s[16:17]
	s_mov_b64 exec, -1
	s_add_u32 s16, s26, 0x2c000
	s_addc_u32 s17, s27, 0
	global_store_dwordx4 v207, v[116:119], s[16:17]
	s_add_u32 s16, s26, 0x58000
	s_addc_u32 s17, s27, 0
	global_store_dwordx4 v207, v[112:115], s[16:17]
	s_add_u32 s16, s26, 0x84000
	s_addc_u32 s17, s27, 0
	global_store_dwordx4 v207, v[108:111], s[16:17]
	v_mul_f32_e32 v232, v8, v178
	v_mul_f32_e32 v233, v9, v178
	v_mul_f32_e32 v234, v10, v178
	v_mul_f32_e32 v235, v11, v178
	s_add_i32 s15, s14, 2
	v_lshl_add_u32 v228, s15, 1, v152
	v_lshl_add_u32 v229, s15, 1, v154
	v_mad_u32_u24 v230, v228, s83, v205
	v_mad_u32_u24 v231, v229, s83, v205
	s_mov_b64 exec, s[8:9]
	global_store_dwordx4 v230, v[16:19], s[86:87] offset:16
	global_store_dwordx4 v230, v[232:235], s[28:29] offset:16
	s_mov_b64 exec, s[10:11]
	global_store_dwordx4 v231, v[0:3], s[30:31] offset:16
	s_mov_b64 exec, -1
	v_fma_f32 v216, v208, v16, v212
	v_fma_f32 v217, v209, v17, v213
	v_fma_f32 v218, v210, v18, v214
	v_fma_f32 v219, v211, v19, v215
	v_fma_f32 v220, v208, v40, v212
	v_fma_f32 v221, v209, v41, v213
	v_fma_f32 v222, v210, v42, v214
	v_fma_f32 v223, v211, v43, v215
	v_fma_f32 v224, v208, v36, v212
	v_fma_f32 v225, v209, v37, v213
	v_fma_f32 v226, v210, v38, v214
	v_fma_f32 v227, v211, v39, v215
	v_fma_f32 v228, v208, v0, v212
	v_fma_f32 v229, v209, v1, v213
	v_fma_f32 v230, v210, v2, v214
	v_fma_f32 v231, v211, v3, v215
	v_fmac_f32_dpp v216, v16, v200 row_shr:1 row_mask:0xf bank_mask:0xf
	v_fmac_f32_dpp v217, v17, v201 row_shr:1 row_mask:0xf bank_mask:0xf
	v_fmac_f32_dpp v218, v18, v202 row_shr:1 row_mask:0xf bank_mask:0xf
	v_fmac_f32_dpp v219, v19, v203 row_shr:1 row_mask:0xf bank_mask:0xf
	v_fmac_f32_dpp v220, v40, v200 row_shr:1 row_mask:0xf bank_mask:0xf
	v_fmac_f32_dpp v221, v41, v201 row_shr:1 row_mask:0xf bank_mask:0xf
	v_fmac_f32_dpp v222, v42, v202 row_shr:1 row_mask:0xf bank_mask:0xf
	v_fmac_f32_dpp v223, v43, v203 row_shr:1 row_mask:0xf bank_mask:0xf
	v_fmac_f32_dpp v224, v36, v200 row_shr:1 row_mask:0xf bank_mask:0xf
	v_fmac_f32_dpp v225, v37, v201 row_shr:1 row_mask:0xf bank_mask:0xf
	v_fmac_f32_dpp v226, v38, v202 row_shr:1 row_mask:0xf bank_mask:0xf
	v_fmac_f32_dpp v227, v39, v203 row_shr:1 row_mask:0xf bank_mask:0xf
	v_fmac_f32_dpp v228, v0, v200 row_shr:1 row_mask:0xf bank_mask:0xf
	v_fmac_f32_dpp v229, v1, v201 row_shr:1 row_mask:0xf bank_mask:0xf
	v_fmac_f32_dpp v230, v2, v202 row_shr:1 row_mask:0xf bank_mask:0xf
	v_fmac_f32_dpp v231, v3, v203 row_shr:1 row_mask:0xf bank_mask:0xf
	v_fmac_f32_dpp v216, v16, v196 row_shr:2 row_mask:0xf bank_mask:0xf
	v_fmac_f32_dpp v217, v17, v197 row_shr:2 row_mask:0xf bank_mask:0xf
	v_fmac_f32_dpp v218, v18, v198 row_shr:2 row_mask:0xf bank_mask:0xf
	v_fmac_f32_dpp v219, v19, v199 row_shr:2 row_mask:0xf bank_mask:0xf
	v_fmac_f32_dpp v220, v40, v196 row_shr:2 row_mask:0xf bank_mask:0xf
	v_fmac_f32_dpp v221, v41, v197 row_shr:2 row_mask:0xf bank_mask:0xf
	v_fmac_f32_dpp v222, v42, v198 row_shr:2 row_mask:0xf bank_mask:0xf
	v_fmac_f32_dpp v223, v43, v199 row_shr:2 row_mask:0xf bank_mask:0xf
	v_fmac_f32_dpp v224, v36, v196 row_shr:2 row_mask:0xf bank_mask:0xf
	v_fmac_f32_dpp v225, v37, v197 row_shr:2 row_mask:0xf bank_mask:0xf
	v_fmac_f32_dpp v226, v38, v198 row_shr:2 row_mask:0xf bank_mask:0xf
	v_fmac_f32_dpp v227, v39, v199 row_shr:2 row_mask:0xf bank_mask:0xf
	v_fmac_f32_dpp v228, v0, v196 row_shr:2 row_mask:0xf bank_mask:0xf
	v_fmac_f32_dpp v229, v1, v197 row_shr:2 row_mask:0xf bank_mask:0xf
	v_fmac_f32_dpp v230, v2, v198 row_shr:2 row_mask:0xf bank_mask:0xf
	v_fmac_f32_dpp v231, v3, v199 row_shr:2 row_mask:0xf bank_mask:0xf
	v_fmac_f32_dpp v220, v16, v164 row_ror:1 row_mask:0xf bank_mask:0xf
; __device__ __forceinline__ unsigned cvt_pk_bf16(float lo, float hi) { unsigned r; asm volatile("v_cvt_pk_bf16_f32 %0, %1, %2" : "=v"(r) : "v"(lo), "v"(hi)); return r; }
; #define PG8_BAR __builtin_amdgcn_s_barrier()
; template <class Epi>
; __device__ __forceinline__ void gemm_phase(LAS unsigned char* lds, const Gemm g, const Order& S, const Epi& E) {
;     ...
;         if (!has_next) break;
; #pragma unroll
;         for (int a = 0; a < 2; ++a)
; #pragma unroll
;             for (int b = 0; b < 2; ++b)
; #pragma unroll
;                 for (int m = 0; m < 4; ++m)
; #pragma unroll
;                     for (int n = 0; n < 2; ++n) acc[a][b][m][n] = (f32x4){0.f, 0.f, 0.f, 0.f};
;         cur = nxt; cA = nA; cB = nB; ++ui;
;         if (wr == 1) PG8_BAR;
;     __device__ __forceinline__ void operator()(Acc& acc, const Unit& u, int wr, int wc, int fr, int fq) const {
;     ...
;                     for (int m = 0; m < 4; ++m) {
;                         const f32x2 q1 = m >= 1 ? r1[m >= 1 ? m - 1 : 0] : (f32x2){0.f, 0.f}, q2 = m >= 1 ? r2[m >= 1 ? m - 1 : 0] : (f32x2){0.f, 0.f};
;                         f32x2 p1, p2;
;                         p1.x = (fr >= 1) ? r1[m].x : q1.x; p1.y = (fr >= 1) ? r1[m].y : q1.y;
;                         p2.x = (fr >= 2) ? r2[m].x : q2.x; p2.y = (fr >= 2) ? r2[m].y : q2.y;
;                         const f32x2 a = w2p * gm[m] + (w1p * p1 + (w0p * p2 + bbp));
;                         const f32x2 na = a * (-1.4426950408889634f);
;                         f32x2 den; den.x = __builtin_amdgcn_exp2f(na.x); den.y = __builtin_amdgcn_exp2f(na.y);
;                         den = den + 1.0f;
;                         f32x2 rc; rc.x = __builtin_amdgcn_rcpf(den.x); rc.y = __builtin_amdgcn_rcpf(den.y);
;                         const f32x2 up = (f32x2){acc[ai][1][m][n][2 * jp], acc[ai][1][m][n][2 * jp + 1]} * rs[m];
;                         const f32x2 ov = (a * rc) * up;
;                         pk[m][2 * n + jp] = cvt_pk_bf16(ov.x, ov.y);
;                     }
;                 }
;             }
; #pragma unroll
;             for (int m = 0; m < 4; ++m) {
;                 const size_t row = (size_t)(row0 + ai * 128 + m * 16);
;                 if (!(m == 0 && fr < 2)) { u32x4 w; w.x = pk[m][0]; w.y = pk[m][1]; w.z = pk[m][2]; w.w = pk[m][3]; *(u32x4*)(act + row * FF + c0) = w; }
;             }
	v_fmac_f32_dpp v221, v17, v165 row_ror:1 row_mask:0xf bank_mask:0xf
	v_fmac_f32_dpp v222, v18, v166 row_ror:1 row_mask:0xf bank_mask:0xf
	v_fmac_f32_dpp v223, v19, v167 row_ror:1 row_mask:0xf bank_mask:0xf
	v_fmac_f32_dpp v224, v40, v164 row_ror:1 row_mask:0xf bank_mask:0xf
	v_fmac_f32_dpp v225, v41, v165 row_ror:1 row_mask:0xf bank_mask:0xf
	v_fmac_f32_dpp v226, v42, v166 row_ror:1 row_mask:0xf bank_mask:0xf
	v_fmac_f32_dpp v227, v43, v167 row_ror:1 row_mask:0xf bank_mask:0xf
	v_fmac_f32_dpp v228, v36, v164 row_ror:1 row_mask:0xf bank_mask:0xf
	v_fmac_f32_dpp v229, v37, v165 row_ror:1 row_mask:0xf bank_mask:0xf
	v_fmac_f32_dpp v230, v38, v166 row_ror:1 row_mask:0xf bank_mask:0xf
	v_fmac_f32_dpp v231, v39, v167 row_ror:1 row_mask:0xf bank_mask:0xf
	v_fmac_f32_dpp v220, v16, v168 row_ror:2 row_mask:0xf bank_mask:0xf
	v_fmac_f32_dpp v221, v17, v169 row_ror:2 row_mask:0xf bank_mask:0xf
	v_fmac_f32_dpp v222, v18, v170 row_ror:2 row_mask:0xf bank_mask:0xf
	v_fmac_f32_dpp v223, v19, v171 row_ror:2 row_mask:0xf bank_mask:0xf
	v_fmac_f32_dpp v224, v40, v168 row_ror:2 row_mask:0xf bank_mask:0xf
	v_fmac_f32_dpp v225, v41, v169 row_ror:2 row_mask:0xf bank_mask:0xf
	v_fmac_f32_dpp v226, v42, v170 row_ror:2 row_mask:0xf bank_mask:0xf
	v_fmac_f32_dpp v227, v43, v171 row_ror:2 row_mask:0xf bank_mask:0xf
	v_fmac_f32_dpp v228, v36, v168 row_ror:2 row_mask:0xf bank_mask:0xf
	v_fmac_f32_dpp v229, v37, v169 row_ror:2 row_mask:0xf bank_mask:0xf
	v_fmac_f32_dpp v230, v38, v170 row_ror:2 row_mask:0xf bank_mask:0xf
	v_fmac_f32_dpp v231, v39, v171 row_ror:2 row_mask:0xf bank_mask:0xf
	v_exp_f32_e32 v16, v216
	v_exp_f32_e32 v17, v217
	v_exp_f32_e32 v18, v218
	v_exp_f32_e32 v19, v219
	v_exp_f32_e32 v40, v220
	v_exp_f32_e32 v41, v221
	v_exp_f32_e32 v42, v222
	v_exp_f32_e32 v43, v223
	v_exp_f32_e32 v36, v224
	v_exp_f32_e32 v37, v225
	v_exp_f32_e32 v38, v226
	v_exp_f32_e32 v39, v227
	v_exp_f32_e32 v0, v228
	v_exp_f32_e32 v1, v229
	v_exp_f32_e32 v2, v230
	v_exp_f32_e32 v3, v231
	v_add_f32_e32 v16, 1.0, v16
	v_add_f32_e32 v17, 1.0, v17
	v_add_f32_e32 v18, 1.0, v18
	v_add_f32_e32 v19, 1.0, v19
	v_add_f32_e32 v40, 1.0, v40
	v_add_f32_e32 v41, 1.0, v41
	v_add_f32_e32 v42, 1.0, v42
	v_add_f32_e32 v43, 1.0, v43
	v_add_f32_e32 v36, 1.0, v36
	v_add_f32_e32 v37, 1.0, v37
	v_add_f32_e32 v38, 1.0, v38
	v_add_f32_e32 v39, 1.0, v39
	v_add_f32_e32 v0, 1.0, v0
	v_add_f32_e32 v1, 1.0, v1
	v_add_f32_e32 v2, 1.0, v2
	v_add_f32_e32 v3, 1.0, v3
	v_rcp_f32_e32 v16, v16
	v_rcp_f32_e32 v17, v17
	v_rcp_f32_e32 v18, v18
	v_rcp_f32_e32 v19, v19
	v_rcp_f32_e32 v40, v40
	v_rcp_f32_e32 v41, v41
	v_rcp_f32_e32 v42, v42
	v_rcp_f32_e32 v43, v43
	v_rcp_f32_e32 v36, v36
	v_rcp_f32_e32 v37, v37
	v_rcp_f32_e32 v38, v38
	v_rcp_f32_e32 v39, v39
	v_rcp_f32_e32 v0, v0
	v_rcp_f32_e32 v1, v1
	v_rcp_f32_e32 v2, v2
	v_rcp_f32_e32 v3, v3
	v_mul_f32_e32 v8, v8, v186
	v_mul_f32_e32 v9, v9, v186
	v_mul_f32_e32 v10, v10, v186
	v_mul_f32_e32 v11, v11, v186
	v_mul_f32_e32 v32, v32, v188
	v_mul_f32_e32 v33, v33, v188
	v_mul_f32_e32 v34, v34, v188
	v_mul_f32_e32 v35, v35, v188
	v_mul_f32_e32 v28, v28, v190
	v_mul_f32_e32 v29, v29, v190
	v_mul_f32_e32 v30, v30, v190
	v_mul_f32_e32 v31, v31, v190
	v_mul_f32_e32 v20, v20, v192
	v_mul_f32_e32 v21, v21, v192
	v_mul_f32_e32 v22, v22, v192
	v_mul_f32_e32 v23, v23, v192
	v_mul_f32_e32 v216, v216, v16
	v_mul_f32_e32 v217, v217, v17
	v_mul_f32_e32 v218, v218, v18
	v_mul_f32_e32 v219, v219, v19
	v_mul_f32_e32 v220, v220, v40
	v_mul_f32_e32 v221, v221, v41
	v_mul_f32_e32 v222, v222, v42
	v_mul_f32_e32 v223, v223, v43
	v_mul_f32_e32 v224, v224, v36
	v_mul_f32_e32 v225, v225, v37
	v_mul_f32_e32 v226, v226, v38
	v_mul_f32_e32 v227, v227, v39
	v_mul_f32_e32 v228, v228, v0
	v_mul_f32_e32 v229, v229, v1
	v_mul_f32_e32 v230, v230, v2
	v_mul_f32_e32 v231, v231, v3
	v_mul_f32_e32 v216, v216, v8
	v_mul_f32_e32 v217, v217, v9
	v_mul_f32_e32 v218, v218, v10
	v_mul_f32_e32 v219, v219, v11
	v_mul_f32_e32 v220, v220, v32
	v_mul_f32_e32 v221, v221, v33
	v_mul_f32_e32 v222, v222, v34
	v_mul_f32_e32 v223, v223, v35
	v_mul_f32_e32 v224, v224, v28
	v_mul_f32_e32 v225, v225, v29
	v_mul_f32_e32 v226, v226, v30
	v_mul_f32_e32 v227, v227, v31
	v_mul_f32_e32 v228, v228, v20
	v_mul_f32_e32 v229, v229, v21
	v_mul_f32_e32 v230, v230, v22
	v_mul_f32_e32 v231, v231, v23
	v_cvt_pk_bf16_f32 v14, v216, v217
	v_cvt_pk_bf16_f32 v15, v218, v219
	v_cvt_pk_bf16_f32 v54, v220, v221
	v_cvt_pk_bf16_f32 v55, v222, v223
	v_cvt_pk_bf16_f32 v50, v224, v225
	v_cvt_pk_bf16_f32 v51, v226, v227
	v_cvt_pk_bf16_f32 v46, v228, v229
	v_cvt_pk_bf16_f32 v47, v230, v231
	s_add_u32 s16, s26, 0x160000
	s_addc_u32 s17, s27, 0
	s_mov_b64 exec, s[6:7]
	global_store_dwordx4 v207, v[12:15], s[16:17]
	s_mov_b64 exec, -1
	s_add_u32 s16, s26, 0x18c000
	s_addc_u32 s17, s27, 0
	global_store_dwordx4 v207, v[52:55], s[16:17]
	s_add_u32 s16, s26, 0x1b8000
	s_addc_u32 s17, s27, 0
	global_store_dwordx4 v207, v[48:51], s[16:17]
	s_add_u32 s16, s26, 0x1e4000
	s_addc_u32 s17, s27, 0
	global_store_dwordx4 v207, v[44:47], s[16:17]
	s_andn2_b64 vcc, exec, s[12:13]
	s_mov_b64 s[12:13], -1
	s_cbranch_vccnz .LBB0_857
	s_branch .LBB0_877
